# pp_v26 + seams: the workgroups arriving at ordinal nx/2 and 3nx/4 of their XCD issue one early buffer_wbl2 each
# baseline (speedup 1.0000x reference)
.LBB0_510:
	s_cmp_gt_i32 s83, 2
	s_cselect_b64 s[0:1], -1, 0
	s_and_b64 s[4:5], s[10:11], s[0:1]
	v_readlane_b32 s38, v238, 36
	s_andn2_b64 vcc, exec, s[4:5]
	v_readlane_b32 s39, v238, 37
	s_mov_b32 s40, s92
	s_cbranch_vccnz .LBB0_564
	s_waitcnt vmcnt(0)
	s_waitcnt vmcnt(0)
	s_barrier
	s_and_saveexec_b64 s[4:5], s[38:39]
	s_cbranch_execz .LBB0_563
	s_add_u32 s98, s98, 1
	v_mov_b32_e32 v1, 0x25f20
	ds_read_b64 v[2:3], v1
	v_readlane_b32 s6, v238, 18
	v_readlane_b32 s7, v238, 19
	s_lshl_b32 s2, s87, 8
	s_addk_i32 s2, 0x1400
	v_mov_b32_e32 v1, s2
	v_mov_b32_e32 v5, 1
	s_nop 1
	global_atomic_add v1, v1, v5, s[6:7] sc0
	buffer_inv sc1
	s_waitcnt vmcnt(1) lgkmcnt(0)
	v_readfirstlane_b32 s12, v1
	v_readfirstlane_b32 s9, v2
	s_lshr_b32 s11, s9, 1
	s_lshr_b32 s13, s9, 2
	v_readfirstlane_b32 s10, v3
	s_add_u32 s12, s12, 1
	s_mul_i32 s9, s9, s98
	s_mul_i32 s10, s10, s98
	v_mov_b32_e32 v1, 0x3400
	s_cmp_eq_u32 s12, s9
	s_cbranch_scc0 .Lfs0_nl
	buffer_wbl2 sc1
	s_waitcnt vmcnt(0)
	global_atomic_add v1, v5, s[6:7]
	s_branch .Lfs0_spin
.Lfs0_nl:
	s_sub_u32 s11, s9, s11
	s_sub_u32 s13, s9, s13
	s_cmp_eq_u32 s12, s11
	s_cbranch_scc1 .Lfs0_ew
	s_cmp_eq_u32 s12, s13
	s_cbranch_scc0 .Lfs0_spin
.Lfs0_ew:
	buffer_wbl2 sc1

.LBB0_855:
	s_cmp_gt_i32 s83, 4
	s_cselect_b64 s[0:1], -1, 0
	s_and_b64 s[4:5], s[6:7], s[0:1]
	s_andn2_b64 vcc, exec, s[4:5]
	s_cbranch_vccnz .LBB0_909
	s_waitcnt vmcnt(0)
	s_waitcnt vmcnt(0) lgkmcnt(0)
	s_barrier
	s_and_saveexec_b64 s[4:5], s[38:39]
	s_cbranch_execz .LBB0_908
	s_add_u32 s98, s98, 1
	v_mov_b32_e32 v1, 0x25f20
	ds_read_b64 v[2:3], v1
	v_readlane_b32 s6, v238, 18
	v_readlane_b32 s7, v238, 19
	s_lshl_b32 s2, s87, 8
	s_addk_i32 s2, 0x1400
	v_mov_b32_e32 v1, s2
	v_mov_b32_e32 v5, 1
	s_nop 1
	global_atomic_add v1, v1, v5, s[6:7] sc0
	buffer_inv sc1
	s_waitcnt vmcnt(1) lgkmcnt(0)
	v_readfirstlane_b32 s12, v1
	v_readfirstlane_b32 s9, v2
	s_lshr_b32 s11, s9, 1
	s_lshr_b32 s13, s9, 2
	v_readfirstlane_b32 s10, v3
	s_add_u32 s12, s12, 1
	s_mul_i32 s9, s9, s98
	s_mul_i32 s10, s10, s98
	v_mov_b32_e32 v1, 0x3400
	s_cmp_eq_u32 s12, s9
	s_cbranch_scc0 .Lfs1_nl
	buffer_wbl2 sc1
	s_waitcnt vmcnt(0)
	global_atomic_add v1, v5, s[6:7]
	s_branch .Lfs1_spin

.LBB0_959:
	s_cmp_gt_i32 s83, 7
	s_cselect_b64 s[4:5], -1, 0
	s_and_b64 s[0:1], s[0:1], s[4:5]
	s_andn2_b64 vcc, exec, s[0:1]
	s_cbranch_vccnz .LBB0_1013
	s_waitcnt vmcnt(0)
	s_waitcnt vmcnt(0) lgkmcnt(0)
	s_barrier
	s_and_saveexec_b64 s[0:1], s[38:39]
	s_cbranch_execz .LBB0_1012
	s_add_u32 s98, s98, 1
	v_mov_b32_e32 v1, 0x25f20
	ds_read_b64 v[2:3], v1
	v_readlane_b32 s6, v238, 18
	v_readlane_b32 s7, v238, 19
	s_lshl_b32 s2, s87, 8
	s_addk_i32 s2, 0x1400
	v_mov_b32_e32 v1, s2
	v_mov_b32_e32 v5, 1
	s_nop 1
	global_atomic_add v1, v1, v5, s[6:7] sc0
	buffer_inv sc1
	s_waitcnt vmcnt(1) lgkmcnt(0)
	v_readfirstlane_b32 s12, v1
	v_readfirstlane_b32 s9, v2
	s_lshr_b32 s11, s9, 1
	s_lshr_b32 s13, s9, 2
	v_readfirstlane_b32 s10, v3
	s_add_u32 s12, s12, 1
	s_mul_i32 s9, s9, s98
	s_mul_i32 s10, s10, s98
	v_mov_b32_e32 v1, 0x3400
	s_cmp_eq_u32 s12, s9
	s_cbranch_scc0 .Lfs2_nl
	buffer_wbl2 sc1
	s_waitcnt vmcnt(0)
	global_atomic_add v1, v5, s[6:7]
	s_branch .Lfs2_spin

.LBB0_1147:
	s_barrier
	s_waitcnt vmcnt(0)
	v_readlane_b32 s38, v238, 36
	v_readlane_b32 s39, v238, 37
	s_barrier
	s_and_saveexec_b64 s[0:1], s[38:39]
	v_readlane_b32 s86, v238, 47
	v_readlane_b32 s87, v238, 46
	v_readlane_b32 s40, v238, 58
	v_readlane_b32 s93, v238, 48
	v_readlane_b32 s24, v238, 38
	v_readlane_b32 s41, v238, 59
	s_cbranch_execz .LBB0_1199
	s_add_u32 s98, s98, 1
	v_mov_b32_e32 v1, 0x25f20
	ds_read_b64 v[2:3], v1
	v_readlane_b32 s6, v238, 18
	v_readlane_b32 s7, v238, 19
	s_lshl_b32 s2, s87, 8
	s_addk_i32 s2, 0x1400
	v_mov_b32_e32 v1, s2
	v_mov_b32_e32 v5, 1
	s_nop 1
	global_atomic_add v1, v1, v5, s[6:7] sc0
	buffer_inv sc1
	s_waitcnt vmcnt(1) lgkmcnt(0)
	v_readfirstlane_b32 s12, v1
	v_readfirstlane_b32 s9, v2
	s_lshr_b32 s11, s9, 1
	s_lshr_b32 s13, s9, 2
	v_readfirstlane_b32 s10, v3
	s_add_u32 s12, s12, 1
	s_mul_i32 s9, s9, s98
	s_mul_i32 s10, s10, s98
	v_mov_b32_e32 v1, 0x3400
	s_cmp_eq_u32 s12, s9
	s_cbranch_scc0 .Lfs3_nl
	buffer_wbl2 sc1
	s_waitcnt vmcnt(0)
	global_atomic_add v1, v5, s[6:7]
	s_branch .Lfs3_spin

.LBB0_1221:
	s_cmp_gt_i32 s83, 8
	s_cselect_b64 s[0:1], -1, 0
	s_and_b64 s[4:5], s[4:5], s[0:1]
	s_andn2_b64 vcc, exec, s[4:5]
	s_mov_b64 s[60:61], s[38:39]
	s_cbranch_vccnz .LBB0_1275
	s_waitcnt vmcnt(0)
	s_waitcnt vmcnt(0) lgkmcnt(0)
	s_barrier
	s_and_saveexec_b64 s[4:5], s[38:39]
	s_cbranch_execz .LBB0_1274
	s_add_u32 s98, s98, 1
	v_mov_b32_e32 v1, 0x25f20
	ds_read_b64 v[2:3], v1
	v_readlane_b32 s6, v238, 18
	v_readlane_b32 s7, v238, 19
	s_lshl_b32 s2, s87, 8
	s_addk_i32 s2, 0x1400
	v_mov_b32_e32 v1, s2
	v_mov_b32_e32 v5, 1
	s_nop 1
	global_atomic_add v1, v1, v5, s[6:7] sc0
	buffer_inv sc1
	s_waitcnt vmcnt(1) lgkmcnt(0)
	v_readfirstlane_b32 s12, v1
	v_readfirstlane_b32 s9, v2
	s_lshr_b32 s11, s9, 1
	s_lshr_b32 s13, s9, 2
	v_readfirstlane_b32 s10, v3
	s_add_u32 s12, s12, 1
	s_mul_i32 s9, s9, s98
	s_mul_i32 s10, s10, s98
	v_mov_b32_e32 v1, 0x3400
	s_cmp_eq_u32 s12, s9
	s_cbranch_scc0 .Lfs4_nl
	buffer_wbl2 sc1
	s_waitcnt vmcnt(0)
	global_atomic_add v1, v5, s[6:7]
	s_branch .Lfs4_spin

.LBB0_1279:
	s_cmp_gt_i32 s83, 9
	s_cselect_b64 s[0:1], -1, 0
	s_and_b64 s[4:5], s[6:7], s[0:1]
	s_andn2_b64 vcc, exec, s[4:5]
	s_cbranch_vccnz .LBB0_1333
	s_waitcnt vmcnt(0)
	s_waitcnt vmcnt(0) lgkmcnt(0)
	s_barrier
	s_and_saveexec_b64 s[4:5], s[38:39]
	s_cbranch_execz .LBB0_1332
	s_add_u32 s98, s98, 1
	v_mov_b32_e32 v1, 0x25f20
	ds_read_b64 v[2:3], v1
	v_readlane_b32 s6, v238, 18
	v_readlane_b32 s7, v238, 19
	s_lshl_b32 s2, s87, 8
	s_addk_i32 s2, 0x1400
	v_mov_b32_e32 v1, s2
	v_mov_b32_e32 v5, 1
	s_nop 1
	global_atomic_add v1, v1, v5, s[6:7] sc0
	buffer_inv sc1
	s_waitcnt vmcnt(1) lgkmcnt(0)
	v_readfirstlane_b32 s12, v1
	v_readfirstlane_b32 s9, v2
	s_lshr_b32 s11, s9, 1
	s_lshr_b32 s13, s9, 2
	v_readfirstlane_b32 s10, v3
	s_add_u32 s12, s12, 1
	s_mul_i32 s9, s9, s98
	s_mul_i32 s10, s10, s98
	v_mov_b32_e32 v1, 0x3400
	s_cmp_eq_u32 s12, s9
	s_cbranch_scc0 .Lfs5_nl
	buffer_wbl2 sc1
	s_waitcnt vmcnt(0)
	global_atomic_add v1, v5, s[6:7]
	s_branch .Lfs5_spin

.LBB0_1360:
	s_cmp_lt_i32 s82, 11
	s_cselect_b64 s[4:5], -1, 0
	s_cmp_gt_i32 s83, 11
	s_cselect_b64 s[0:1], -1, 0
	s_and_b64 s[4:5], s[4:5], s[0:1]
	s_andn2_b64 vcc, exec, s[4:5]
	s_cbranch_vccnz .LBB0_1414
	s_waitcnt vmcnt(0)
	s_waitcnt vmcnt(0) lgkmcnt(0)
	s_barrier
	s_and_saveexec_b64 s[4:5], s[38:39]
	s_cbranch_execz .LBB0_1413
	s_add_u32 s98, s98, 1
	v_mov_b32_e32 v1, 0x25f20
	ds_read_b64 v[2:3], v1
	v_readlane_b32 s6, v238, 18
	v_readlane_b32 s7, v238, 19
	s_lshl_b32 s2, s87, 8
	s_addk_i32 s2, 0x1400
	v_mov_b32_e32 v1, s2
	v_mov_b32_e32 v5, 1
	s_nop 1
	global_atomic_add v1, v1, v5, s[6:7] sc0
	buffer_inv sc1
	s_waitcnt vmcnt(1) lgkmcnt(0)
	v_readfirstlane_b32 s12, v1
	v_readfirstlane_b32 s9, v2
	s_lshr_b32 s11, s9, 1
	s_lshr_b32 s13, s9, 2
	v_readfirstlane_b32 s10, v3
	s_add_u32 s12, s12, 1
	s_mul_i32 s9, s9, s98
	s_mul_i32 s10, s10, s98
	v_mov_b32_e32 v1, 0x3400
	s_cmp_eq_u32 s12, s9
	s_cbranch_scc0 .Lfs6_nl
	buffer_wbl2 sc1
	s_waitcnt vmcnt(0)
	global_atomic_add v1, v5, s[6:7]
	s_branch .Lfs6_spin

.LBB0_1457:
	s_cmp_gt_i32 s83, 12
	s_cselect_b64 s[0:1], -1, 0
	s_and_b64 s[4:5], s[6:7], s[0:1]
	s_andn2_b64 vcc, exec, s[4:5]
	s_cbranch_vccnz .LBB0_1511
	s_waitcnt vmcnt(0)
	s_waitcnt vmcnt(0) lgkmcnt(0)
	s_barrier
	s_and_saveexec_b64 s[4:5], s[38:39]
	s_cbranch_execz .LBB0_1510
	s_add_u32 s98, s98, 1
	v_mov_b32_e32 v1, 0x25f20
	ds_read_b64 v[2:3], v1
	v_readlane_b32 s6, v238, 18
	v_readlane_b32 s7, v238, 19
	s_lshl_b32 s2, s87, 8
	s_addk_i32 s2, 0x1400
	v_mov_b32_e32 v1, s2
	v_mov_b32_e32 v5, 1
	s_nop 1
	global_atomic_add v1, v1, v5, s[6:7] sc0
	buffer_inv sc1
	s_waitcnt vmcnt(1) lgkmcnt(0)
	v_readfirstlane_b32 s12, v1
	v_readfirstlane_b32 s9, v2
	s_lshr_b32 s11, s9, 1
	s_lshr_b32 s13, s9, 2
	v_readfirstlane_b32 s10, v3
	s_add_u32 s12, s12, 1
	s_mul_i32 s9, s9, s98
	s_mul_i32 s10, s10, s98
	v_mov_b32_e32 v1, 0x3400
	s_cmp_eq_u32 s12, s9
	s_cbranch_scc0 .Lfs7_nl
	buffer_wbl2 sc1
	s_waitcnt vmcnt(0)
	global_atomic_add v1, v5, s[6:7]
	s_branch .Lfs7_spin

.LBB0_1528:
	s_cmp_gt_i32 s83, 13
	s_cselect_b64 s[0:1], -1, 0
	s_and_b64 s[4:5], s[4:5], s[0:1]
	s_andn2_b64 vcc, exec, s[4:5]
	s_cbranch_vccnz .LBB0_1582
	s_waitcnt vmcnt(0)
	s_waitcnt vmcnt(0) lgkmcnt(0)
	s_barrier
	s_and_saveexec_b64 s[4:5], s[38:39]
	s_cbranch_execz .LBB0_1581
	s_add_u32 s98, s98, 1
	v_mov_b32_e32 v1, 0x25f20
	ds_read_b64 v[2:3], v1
	v_readlane_b32 s6, v238, 18
	v_readlane_b32 s7, v238, 19
	s_lshl_b32 s2, s87, 8
	s_addk_i32 s2, 0x1400
	v_mov_b32_e32 v1, s2
	v_mov_b32_e32 v5, 1
	s_nop 1
	global_atomic_add v1, v1, v5, s[6:7] sc0
	buffer_inv sc1
	s_waitcnt vmcnt(1) lgkmcnt(0)
	v_readfirstlane_b32 s12, v1
	v_readfirstlane_b32 s9, v2
	s_lshr_b32 s11, s9, 1
	s_lshr_b32 s13, s9, 2
	v_readfirstlane_b32 s10, v3
	s_add_u32 s12, s12, 1
	s_mul_i32 s9, s9, s98
	s_mul_i32 s10, s10, s98
	v_mov_b32_e32 v1, 0x3400
	s_cmp_eq_u32 s12, s9
	s_cbranch_scc0 .Lfs8_nl
	buffer_wbl2 sc1
	s_waitcnt vmcnt(0)
	global_atomic_add v1, v5, s[6:7]
	s_branch .Lfs8_spin
